# adds P5 epilogue f32 store coalescing (ds_bpermute lane permutation of address and data, 4 lanes per 64B row piece) on top of v016
# speedup vs baseline: 1.0208x; 1.0033x over previous
;     DEVI void init() { G = gridDim.x; const int b = blockIdx.x; if ((G & 7) == 0) { x = b & 7; j = b >> 3; nloc = G >> 3; } else { x = -1; j = b; nloc = G; } }
;     DEVI void init(bool pr) { pair = pr; G = gridDim.x; const int b = blockIdx.x; if ((G & 7) == 0) { x = b & 7; j = b >> 3; nloc = G >> 3; } else { x = -1; j = b; nloc = G; } }
;     DEVI void operator()(const f32x4 (&acc)[2][2][4][2], const pg8::Unit& u, int wr, int wc, int l15, int g) const {
;         const int colb = u.pn * 256 + 32 * wc + 4 * g;
; template <int PH>
; DEVI void run_phase(const Params& p, unsigned char* smem) {
;     ...
;         EpiY epi; epi.pp = &p;
;         pg8::Gemm g{(const bf16_t*)(p.ws + W_XN), (const bf16_t*)(p.ws + W_WOT), nullptr, nullptr, 1024};
;         OrderP4 S; S.init(false);
;         pg8::gemm_phase(lds, g, S, epi);
.LBB0_1210:
	v_and_b32_e32 v238, 63, v203
	v_and_b32_e32 v239, 3, v238
	v_lshrrev_b32_e32 v237, 4, v238
	v_bfe_u32 v236, v238, 2, 2
	v_lshl_add_u32 v237, v237, 2, v236
	v_lshl_add_u32 v238, v239, 4, v237
	v_lshlrev_b32_e32 v238, 2, v238
	s_and_b64 vcc, exec, s[78:79]
	v_readfirstlane_b32 s6, v203
	s_cbranch_vccz .LBB0_1252
	s_cmpk_lt_i32 s91, 0x200
	s_cselect_b64 s[0:1], -1, 0
	s_cbranch_execnz .LBB0_1213

;     DEVI void operator()(const f32x4 (&acc)[2][2][4][2], const pg8::Unit& u, int wr, int wc, int l15, int g) const {
;     ...
; #pragma unroll
;             for (int m = 2 * mh; m < 2 * mh + 2; ++m) {
;                 const int tok = u.pm * 256 + 128 * ai + 64 * wr + 16 * m + l15;
;                 const float* xr = (tok < NTP) ? pp->x_p + (size_t)tok * 1024 : pp->x_s + (size_t)(tok - NTP) * 1024;
; #pragma unroll
;                 for (int bj = 0; bj < 2; ++bj)
; #pragma unroll
;                     for (int n = 0; n < 2; ++n) xv[m][bj][n] = *(const f32x4*)(xr + colb + 128 * bj + 16 * n);
;             }
; #pragma unroll
;             for (int m = 2 * mh; m < 2 * mh + 2; ++m) {
;                 const int tok = u.pm * 256 + 128 * ai + 64 * wr + 16 * m + l15;
; #pragma unroll
;                 for (int bj = 0; bj < 2; ++bj)
; #pragma unroll
;                     for (int n = 0; n < 2; ++n) *(f32x4*)(pp->out + (size_t)tok * 1024 + colb + 128 * bj + 16 * n) = xv[m][bj][n] + acc[ai][bj][m][n];
;             }
.LBB0_1235:
	s_or_b64 exec, exec, s[18:19]
	v_lshlrev_b64 v[154:155], 2, v[154:155]
	v_lshl_add_u64 v[178:179], v[162:163], 0, v[154:155]
	global_load_dwordx4 v[160:163], v[178:179], off
	global_load_dwordx4 v[170:173], v[178:179], off offset:64
	global_load_dwordx4 v[174:177], v[178:179], off offset:512
	s_nop 0
	global_load_dwordx4 v[178:181], v[178:179], off offset:576
	v_readlane_b32 s44, v234, 24
	v_readlane_b32 s45, v234, 25
	v_readlane_b32 s46, v234, 26
	v_readlane_b32 s47, v234, 27
	v_readlane_b32 s48, v234, 28
	v_readlane_b32 s49, v234, 29
	v_readlane_b32 s50, v234, 30
	v_readlane_b32 s51, v234, 31
	v_readlane_b32 s52, v234, 32
	v_readlane_b32 s53, v234, 33
	v_readlane_b32 s54, v234, 34
	v_readlane_b32 s55, v234, 35
	v_readlane_b32 s56, v234, 36
	v_readlane_b32 s57, v234, 37
	v_readlane_b32 s58, v234, 38
	v_readlane_b32 s59, v234, 39
	v_lshlrev_b64 v[182:183], 12, v[156:157]
	s_waitcnt vmcnt(0)
	v_pk_add_f32 v[128:129], v[112:113], v[128:129]
	s_mov_b64 s[18:19], s[58:59]
	v_or_b32_e32 v112, 32, v156
	v_readlane_b32 s44, v234, 2
	v_pk_add_f32 v[118:119], v[118:119], v[134:135]
	v_pk_add_f32 v[116:117], v[116:117], v[132:133]
	v_add_u32_e32 v134, 0xffff8020, v156
	v_readlane_b32 s45, v234, 3
	v_readlane_b32 s46, v234, 4
	v_readlane_b32 s47, v234, 5
	v_lshl_add_u64 v[132:133], s[18:19], 0, v[182:183]
	v_ashrrev_i32_e32 v113, 31, v112
	v_cmp_gt_i32_e32 vcc, s35, v112
	v_pk_add_f32 v[126:127], v[126:127], v[142:143]
	v_pk_add_f32 v[124:125], v[124:125], v[140:141]
	v_pk_add_f32 v[122:123], v[122:123], v[138:139]
	v_pk_add_f32 v[120:121], v[120:121], v[136:137]
	v_mov_b32_e32 v136, s47
	v_mov_b32_e32 v137, s45
	v_mov_b32_e32 v138, s46
	v_mov_b32_e32 v139, s44
	v_lshl_add_u64 v[132:133], v[132:133], 0, v[154:155]
	v_cndmask_b32_e32 v135, 0, v113, vcc
	v_cndmask_b32_e32 v134, v134, v112, vcc
	v_pk_add_f32 v[130:131], v[114:115], v[130:131]
	v_lshl_add_u64 v[114:115], s[18:19], 0, v[158:159]
	v_cndmask_b32_e32 v137, v136, v137, vcc
	v_cndmask_b32_e32 v136, v138, v139, vcc
	ds_bpermute_b32 v236, v238, v132
	ds_bpermute_b32 v237, v238, v133
	ds_bpermute_b32 v240, v238, v124
	ds_bpermute_b32 v241, v238, v125
	ds_bpermute_b32 v242, v238, v126
	ds_bpermute_b32 v243, v238, v127
	ds_bpermute_b32 v244, v238, v120
	ds_bpermute_b32 v245, v238, v121
	ds_bpermute_b32 v246, v238, v122
	ds_bpermute_b32 v247, v238, v123
	s_waitcnt lgkmcnt(4)
	global_store_dwordx4 v[236:237], v[240:243], off
	ds_bpermute_b32 v248, v238, v116
	ds_bpermute_b32 v249, v238, v117
	ds_bpermute_b32 v250, v238, v118
	ds_bpermute_b32 v251, v238, v119
	s_waitcnt lgkmcnt(4)
	global_store_dwordx4 v[236:237], v[244:247], off offset:64
	ds_bpermute_b32 v252, v238, v128
	ds_bpermute_b32 v253, v238, v129
	ds_bpermute_b32 v254, v238, v130
	ds_bpermute_b32 v255, v238, v131
	s_waitcnt lgkmcnt(4)
	global_store_dwordx4 v[236:237], v[248:251], off offset:512
	s_waitcnt lgkmcnt(0)
	global_store_dwordx4 v[236:237], v[252:255], off offset:576
	v_lshl_add_u64 v[114:115], v[114:115], 0, v[154:155]
	v_lshlrev_b64 v[116:117], 12, v[134:135]
	v_lshl_add_u64 v[116:117], v[136:137], 0, v[116:117]
	v_lshl_add_u64 v[116:117], v[116:117], 0, v[154:155]
	v_readlane_b32 s48, v234, 6
	v_readlane_b32 s49, v234, 7
	v_readlane_b32 s50, v234, 8
	v_readlane_b32 s51, v234, 9
	v_readlane_b32 s52, v234, 10
	v_readlane_b32 s53, v234, 11
	v_readlane_b32 s54, v234, 12
	v_readlane_b32 s55, v234, 13
	v_readlane_b32 s56, v234, 14
	v_readlane_b32 s57, v234, 15
	v_readlane_b32 s58, v234, 16
	v_readlane_b32 s59, v234, 17
	v_pk_add_f32 v[110:111], v[110:111], v[162:163]
	v_pk_add_f32 v[108:109], v[108:109], v[160:161]
	v_pk_add_f32 v[106:107], v[106:107], v[172:173]
	v_pk_add_f32 v[104:105], v[104:105], v[170:171]
	v_pk_add_f32 v[102:103], v[102:103], v[176:177]
	v_pk_add_f32 v[100:101], v[100:101], v[174:175]
	v_pk_add_f32 v[98:99], v[98:99], v[180:181]
	v_pk_add_f32 v[96:97], v[96:97], v[178:179]
	ds_bpermute_b32 v236, v238, v114
	ds_bpermute_b32 v237, v238, v115
	ds_bpermute_b32 v240, v238, v108
	ds_bpermute_b32 v241, v238, v109
	ds_bpermute_b32 v242, v238, v110
	ds_bpermute_b32 v243, v238, v111
	ds_bpermute_b32 v244, v238, v104
	ds_bpermute_b32 v245, v238, v105
	ds_bpermute_b32 v246, v238, v106
	ds_bpermute_b32 v247, v238, v107
	s_waitcnt lgkmcnt(4)
	global_store_dwordx4 v[236:237], v[240:243], off
	ds_bpermute_b32 v248, v238, v100
	ds_bpermute_b32 v249, v238, v101
	ds_bpermute_b32 v250, v238, v102
	ds_bpermute_b32 v251, v238, v103
	s_waitcnt lgkmcnt(4)
	global_store_dwordx4 v[236:237], v[244:247], off offset:64
	ds_bpermute_b32 v252, v238, v96
	ds_bpermute_b32 v253, v238, v97
	ds_bpermute_b32 v254, v238, v98
	ds_bpermute_b32 v255, v238, v99
	s_waitcnt lgkmcnt(4)
	global_store_dwordx4 v[236:237], v[248:251], off offset:512
	s_waitcnt lgkmcnt(0)
	global_store_dwordx4 v[236:237], v[252:255], off offset:576
	global_load_dwordx4 v[108:111], v[116:117], off
	s_nop 0
	global_load_dwordx4 v[104:107], v[116:117], off offset:64
	global_load_dwordx4 v[100:103], v[116:117], off offset:512
	global_load_dwordx4 v[96:99], v[116:117], off offset:576
	v_or_b32_e32 v116, 48, v156
	v_cmp_lt_i32_e32 vcc, s40, v116
	s_and_saveexec_b64 s[18:19], vcc
	s_xor_b64 s[18:19], exec, s[18:19]
	s_cbranch_execz .LBB0_1237
	v_add_u32_e32 v148, 0xffff8030, v156
	v_readlane_b32 s44, v234, 2
	v_lshlrev_b64 v[114:115], 12, v[148:149]
	v_readlane_b32 s46, v234, 4
	v_readlane_b32 s47, v234, 5
	v_mov_b32_e32 v117, v149
	v_readlane_b32 s45, v234, 3
	v_lshl_add_u64 v[118:119], s[46:47], 0, v[114:115]
	v_lshlrev_b64 v[114:115], 12, v[116:117]
	v_readlane_b32 s48, v234, 6
	v_readlane_b32 s49, v234, 7
	v_readlane_b32 s50, v234, 8
	v_readlane_b32 s51, v234, 9
	v_readlane_b32 s52, v234, 10
	v_readlane_b32 s53, v234, 11
	v_readlane_b32 s54, v234, 12
	v_readlane_b32 s55, v234, 13
	v_readlane_b32 s56, v234, 14
	v_readlane_b32 s57, v234, 15
	v_readlane_b32 s58, v234, 16
	v_readlane_b32 s59, v234, 17

;     DEVI void operator()(const f32x4 (&acc)[2][2][4][2], const pg8::Unit& u, int wr, int wc, int l15, int g) const {
;     ...
; #pragma unroll
;             for (int m = 2 * mh; m < 2 * mh + 2; ++m) {
;                 const int tok = u.pm * 256 + 128 * ai + 64 * wr + 16 * m + l15;
;                 const float* xr = (tok < NTP) ? pp->x_p + (size_t)tok * 1024 : pp->x_s + (size_t)(tok - NTP) * 1024;
; #pragma unroll
;                 for (int bj = 0; bj < 2; ++bj)
; #pragma unroll
;                     for (int n = 0; n < 2; ++n) xv[m][bj][n] = *(const f32x4*)(xr + colb + 128 * bj + 16 * n);
;             }
; #pragma unroll
;             for (int m = 2 * mh; m < 2 * mh + 2; ++m) {
;                 const int tok = u.pm * 256 + 128 * ai + 64 * wr + 16 * m + l15;
; #pragma unroll
;                 for (int bj = 0; bj < 2; ++bj)
; #pragma unroll
;                     for (int n = 0; n < 2; ++n) *(f32x4*)(pp->out + (size_t)tok * 1024 + colb + 128 * bj + 16 * n) = xv[m][bj][n] + acc[ai][bj][m][n];
;             }
.LBB0_1239:
	s_or_b64 exec, exec, s[18:19]
	v_lshl_add_u64 v[128:129], v[118:119], 0, v[154:155]
	global_load_dwordx4 v[116:119], v[128:129], off
	global_load_dwordx4 v[120:123], v[128:129], off offset:64
	global_load_dwordx4 v[124:127], v[128:129], off offset:512
	s_nop 0
	global_load_dwordx4 v[128:131], v[128:129], off offset:576
	v_readlane_b32 s44, v234, 24
	v_readlane_b32 s45, v234, 25
	v_readlane_b32 s46, v234, 26
	v_readlane_b32 s47, v234, 27
	v_readlane_b32 s48, v234, 28
	v_readlane_b32 s49, v234, 29
	v_readlane_b32 s50, v234, 30
	v_readlane_b32 s51, v234, 31
	v_readlane_b32 s52, v234, 32
	v_readlane_b32 s53, v234, 33
	v_readlane_b32 s54, v234, 34
	v_readlane_b32 s55, v234, 35
	v_readlane_b32 s56, v234, 36
	v_readlane_b32 s57, v234, 37
	v_readlane_b32 s58, v234, 38
	v_readlane_b32 s59, v234, 39
	v_lshlrev_b64 v[112:113], 12, v[112:113]
	s_waitcnt vmcnt(4)
	v_pk_add_f32 v[96:97], v[80:81], v[96:97]
	s_mov_b64 s[18:19], s[58:59]
	v_add_u32_e32 v80, 0x80, v156
	v_readlane_b32 s44, v234, 2
	v_pk_add_f32 v[86:87], v[86:87], v[102:103]
	v_pk_add_f32 v[84:85], v[84:85], v[100:101]
	v_add_u32_e32 v102, 0xffff8080, v156
	v_readlane_b32 s45, v234, 3
	v_readlane_b32 s46, v234, 4
	v_readlane_b32 s47, v234, 5
	v_lshl_add_u64 v[100:101], s[18:19], 0, v[112:113]
	v_ashrrev_i32_e32 v81, 31, v80
	v_cmp_gt_i32_e32 vcc, s35, v80
	v_pk_add_f32 v[94:95], v[94:95], v[110:111]
	v_pk_add_f32 v[92:93], v[92:93], v[108:109]
	v_pk_add_f32 v[90:91], v[90:91], v[106:107]
	v_pk_add_f32 v[88:89], v[88:89], v[104:105]
	v_mov_b32_e32 v104, s47
	v_mov_b32_e32 v105, s45
	v_mov_b32_e32 v106, s46
	v_mov_b32_e32 v107, s44
	v_lshl_add_u64 v[100:101], v[100:101], 0, v[154:155]
	v_cndmask_b32_e32 v103, 0, v81, vcc
	v_cndmask_b32_e32 v102, v102, v80, vcc
	v_pk_add_f32 v[98:99], v[82:83], v[98:99]
	v_lshl_add_u64 v[82:83], s[18:19], 0, v[114:115]
	v_cndmask_b32_e32 v105, v104, v105, vcc
	v_cndmask_b32_e32 v104, v106, v107, vcc
	ds_bpermute_b32 v236, v238, v100
	ds_bpermute_b32 v237, v238, v101
	ds_bpermute_b32 v240, v238, v92
	ds_bpermute_b32 v241, v238, v93
	ds_bpermute_b32 v242, v238, v94
	ds_bpermute_b32 v243, v238, v95
	ds_bpermute_b32 v244, v238, v88
	ds_bpermute_b32 v245, v238, v89
	ds_bpermute_b32 v246, v238, v90
	ds_bpermute_b32 v247, v238, v91
	s_waitcnt lgkmcnt(4)
	global_store_dwordx4 v[236:237], v[240:243], off
	ds_bpermute_b32 v248, v238, v84
	ds_bpermute_b32 v249, v238, v85
	ds_bpermute_b32 v250, v238, v86
	ds_bpermute_b32 v251, v238, v87
	s_waitcnt lgkmcnt(4)
	global_store_dwordx4 v[236:237], v[244:247], off offset:64
	ds_bpermute_b32 v252, v238, v96
	ds_bpermute_b32 v253, v238, v97
	ds_bpermute_b32 v254, v238, v98
	ds_bpermute_b32 v255, v238, v99
	s_waitcnt lgkmcnt(4)
	global_store_dwordx4 v[236:237], v[248:251], off offset:512
	s_waitcnt lgkmcnt(0)
	global_store_dwordx4 v[236:237], v[252:255], off offset:576
	v_lshl_add_u64 v[82:83], v[82:83], 0, v[154:155]
	v_lshlrev_b64 v[84:85], 12, v[102:103]
	v_lshl_add_u64 v[84:85], v[104:105], 0, v[84:85]
	v_lshl_add_u64 v[84:85], v[84:85], 0, v[154:155]
	v_readlane_b32 s48, v234, 6
	v_readlane_b32 s49, v234, 7
	v_readlane_b32 s50, v234, 8
	v_readlane_b32 s51, v234, 9
	v_readlane_b32 s52, v234, 10
	v_readlane_b32 s53, v234, 11
	v_readlane_b32 s54, v234, 12
	v_readlane_b32 s55, v234, 13
	v_readlane_b32 s56, v234, 14
	v_readlane_b32 s57, v234, 15
	v_readlane_b32 s58, v234, 16
	v_readlane_b32 s59, v234, 17
	s_waitcnt vmcnt(7)
	v_pk_add_f32 v[78:79], v[78:79], v[118:119]
	v_pk_add_f32 v[76:77], v[76:77], v[116:117]
	s_waitcnt vmcnt(6)
	v_pk_add_f32 v[74:75], v[74:75], v[122:123]
	v_pk_add_f32 v[72:73], v[72:73], v[120:121]
	s_waitcnt vmcnt(5)
	v_pk_add_f32 v[70:71], v[70:71], v[126:127]
	v_pk_add_f32 v[68:69], v[68:69], v[124:125]
	s_waitcnt vmcnt(4)
	v_pk_add_f32 v[66:67], v[66:67], v[130:131]
	v_pk_add_f32 v[64:65], v[64:65], v[128:129]
	ds_bpermute_b32 v236, v238, v82
	ds_bpermute_b32 v237, v238, v83
	ds_bpermute_b32 v240, v238, v76
	ds_bpermute_b32 v241, v238, v77
	ds_bpermute_b32 v242, v238, v78
	ds_bpermute_b32 v243, v238, v79
	ds_bpermute_b32 v244, v238, v72
	ds_bpermute_b32 v245, v238, v73
	ds_bpermute_b32 v246, v238, v74
	ds_bpermute_b32 v247, v238, v75
	s_waitcnt lgkmcnt(4)
	global_store_dwordx4 v[236:237], v[240:243], off
	ds_bpermute_b32 v248, v238, v68
	ds_bpermute_b32 v249, v238, v69
	ds_bpermute_b32 v250, v238, v70
	ds_bpermute_b32 v251, v238, v71
	s_waitcnt lgkmcnt(4)
	global_store_dwordx4 v[236:237], v[244:247], off offset:64
	ds_bpermute_b32 v252, v238, v64
	ds_bpermute_b32 v253, v238, v65
	ds_bpermute_b32 v254, v238, v66
	ds_bpermute_b32 v255, v238, v67
	s_waitcnt lgkmcnt(4)
	global_store_dwordx4 v[236:237], v[248:251], off offset:512
	s_waitcnt lgkmcnt(0)
	global_store_dwordx4 v[236:237], v[252:255], off offset:576
	global_load_dwordx4 v[76:79], v[84:85], off
	s_nop 0
	global_load_dwordx4 v[72:75], v[84:85], off offset:64
	global_load_dwordx4 v[68:71], v[84:85], off offset:512
	global_load_dwordx4 v[64:67], v[84:85], off offset:576
	v_add_u32_e32 v84, 0x90, v156
	v_cmp_lt_i32_e32 vcc, s40, v84
	s_and_saveexec_b64 s[18:19], vcc
	s_xor_b64 s[18:19], exec, s[18:19]
	s_cbranch_execz .LBB0_1241
	v_add_u32_e32 v148, 0xffff8090, v156
	v_readlane_b32 s44, v234, 2
	v_lshlrev_b64 v[82:83], 12, v[148:149]
	v_readlane_b32 s46, v234, 4
	v_readlane_b32 s47, v234, 5
	v_mov_b32_e32 v85, v149
	v_readlane_b32 s45, v234, 3
	v_lshl_add_u64 v[86:87], s[46:47], 0, v[82:83]
	v_lshlrev_b64 v[82:83], 12, v[84:85]
	v_readlane_b32 s48, v234, 6
	v_readlane_b32 s49, v234, 7
	v_readlane_b32 s50, v234, 8
	v_readlane_b32 s51, v234, 9
	v_readlane_b32 s52, v234, 10
	v_readlane_b32 s53, v234, 11
	v_readlane_b32 s54, v234, 12
	v_readlane_b32 s55, v234, 13
	v_readlane_b32 s56, v234, 14
	v_readlane_b32 s57, v234, 15
	v_readlane_b32 s58, v234, 16
	v_readlane_b32 s59, v234, 17

;     DEVI void operator()(const f32x4 (&acc)[2][2][4][2], const pg8::Unit& u, int wr, int wc, int l15, int g) const {
;     ...
; #pragma unroll
;             for (int m = 2 * mh; m < 2 * mh + 2; ++m) {
;                 const int tok = u.pm * 256 + 128 * ai + 64 * wr + 16 * m + l15;
;                 const float* xr = (tok < NTP) ? pp->x_p + (size_t)tok * 1024 : pp->x_s + (size_t)(tok - NTP) * 1024;
; #pragma unroll
;                 for (int bj = 0; bj < 2; ++bj)
; #pragma unroll
;                     for (int n = 0; n < 2; ++n) xv[m][bj][n] = *(const f32x4*)(xr + colb + 128 * bj + 16 * n);
;             }
; #pragma unroll
;             for (int m = 2 * mh; m < 2 * mh + 2; ++m) {
;                 const int tok = u.pm * 256 + 128 * ai + 64 * wr + 16 * m + l15;
; #pragma unroll
;                 for (int bj = 0; bj < 2; ++bj)
; #pragma unroll
;                     for (int n = 0; n < 2; ++n) *(f32x4*)(pp->out + (size_t)tok * 1024 + colb + 128 * bj + 16 * n) = xv[m][bj][n] + acc[ai][bj][m][n];
;             }
.LBB0_1243:
	s_or_b64 exec, exec, s[18:19]
	v_lshl_add_u64 v[100:101], v[86:87], 0, v[154:155]
	global_load_dwordx4 v[84:87], v[100:101], off
	global_load_dwordx4 v[88:91], v[100:101], off offset:64
	global_load_dwordx4 v[92:95], v[100:101], off offset:512
	global_load_dwordx4 v[96:99], v[100:101], off offset:576
	v_readlane_b32 s44, v234, 24
	v_readlane_b32 s45, v234, 25
	v_readlane_b32 s46, v234, 26
	v_readlane_b32 s47, v234, 27
	v_readlane_b32 s48, v234, 28
	v_readlane_b32 s49, v234, 29
	v_readlane_b32 s50, v234, 30
	v_readlane_b32 s51, v234, 31
	v_readlane_b32 s52, v234, 32
	v_readlane_b32 s53, v234, 33
	v_readlane_b32 s54, v234, 34
	v_readlane_b32 s55, v234, 35
	v_readlane_b32 s56, v234, 36
	v_readlane_b32 s57, v234, 37
	v_readlane_b32 s58, v234, 38
	v_readlane_b32 s59, v234, 39
	v_lshlrev_b64 v[80:81], 12, v[80:81]
	s_waitcnt vmcnt(4)
	v_pk_add_f32 v[64:65], v[48:49], v[64:65]
	s_mov_b64 s[18:19], s[58:59]
	v_add_u32_e32 v48, 0xa0, v156
	v_readlane_b32 s44, v234, 2
	v_pk_add_f32 v[54:55], v[54:55], v[70:71]
	v_pk_add_f32 v[52:53], v[52:53], v[68:69]
	v_add_u32_e32 v70, 0xffff80a0, v156
	v_readlane_b32 s45, v234, 3
	v_readlane_b32 s46, v234, 4
	v_readlane_b32 s47, v234, 5
	v_lshl_add_u64 v[68:69], s[18:19], 0, v[80:81]
	v_ashrrev_i32_e32 v49, 31, v48
	v_cmp_gt_i32_e32 vcc, s35, v48
	v_pk_add_f32 v[62:63], v[62:63], v[78:79]
	v_pk_add_f32 v[60:61], v[60:61], v[76:77]
	v_pk_add_f32 v[58:59], v[58:59], v[74:75]
	v_pk_add_f32 v[56:57], v[56:57], v[72:73]
	v_mov_b32_e32 v72, s47
	v_mov_b32_e32 v73, s45
	v_mov_b32_e32 v74, s46
	v_mov_b32_e32 v75, s44
	v_lshl_add_u64 v[68:69], v[68:69], 0, v[154:155]
	v_cndmask_b32_e32 v71, 0, v49, vcc
	v_cndmask_b32_e32 v70, v70, v48, vcc
	v_pk_add_f32 v[66:67], v[50:51], v[66:67]
	v_lshl_add_u64 v[50:51], s[18:19], 0, v[82:83]
	v_cndmask_b32_e32 v73, v72, v73, vcc
	v_cndmask_b32_e32 v72, v74, v75, vcc
	ds_bpermute_b32 v236, v238, v68
	ds_bpermute_b32 v237, v238, v69
	ds_bpermute_b32 v240, v238, v60
	ds_bpermute_b32 v241, v238, v61
	ds_bpermute_b32 v242, v238, v62
	ds_bpermute_b32 v243, v238, v63
	ds_bpermute_b32 v244, v238, v56
	ds_bpermute_b32 v245, v238, v57
	ds_bpermute_b32 v246, v238, v58
	ds_bpermute_b32 v247, v238, v59
	s_waitcnt lgkmcnt(4)
	global_store_dwordx4 v[236:237], v[240:243], off
	ds_bpermute_b32 v248, v238, v52
	ds_bpermute_b32 v249, v238, v53
	ds_bpermute_b32 v250, v238, v54
	ds_bpermute_b32 v251, v238, v55
	s_waitcnt lgkmcnt(4)
	global_store_dwordx4 v[236:237], v[244:247], off offset:64
	ds_bpermute_b32 v252, v238, v64
	ds_bpermute_b32 v253, v238, v65
	ds_bpermute_b32 v254, v238, v66
	ds_bpermute_b32 v255, v238, v67
	s_waitcnt lgkmcnt(4)
	global_store_dwordx4 v[236:237], v[248:251], off offset:512
	s_waitcnt lgkmcnt(0)
	global_store_dwordx4 v[236:237], v[252:255], off offset:576
	v_lshl_add_u64 v[50:51], v[50:51], 0, v[154:155]
	v_lshlrev_b64 v[52:53], 12, v[70:71]
	v_lshl_add_u64 v[52:53], v[72:73], 0, v[52:53]
	v_lshl_add_u64 v[52:53], v[52:53], 0, v[154:155]
	v_readlane_b32 s48, v234, 6
	v_readlane_b32 s49, v234, 7
	v_readlane_b32 s50, v234, 8
	v_readlane_b32 s51, v234, 9
	v_readlane_b32 s52, v234, 10
	v_readlane_b32 s53, v234, 11
	v_readlane_b32 s54, v234, 12
	v_readlane_b32 s55, v234, 13
	v_readlane_b32 s56, v234, 14
	v_readlane_b32 s57, v234, 15
	v_readlane_b32 s58, v234, 16
	v_readlane_b32 s59, v234, 17
	s_waitcnt vmcnt(7)
	v_pk_add_f32 v[46:47], v[46:47], v[86:87]
	v_pk_add_f32 v[44:45], v[44:45], v[84:85]
	s_waitcnt vmcnt(6)
	v_pk_add_f32 v[42:43], v[42:43], v[90:91]
	v_pk_add_f32 v[40:41], v[40:41], v[88:89]
	s_waitcnt vmcnt(5)
	v_pk_add_f32 v[38:39], v[38:39], v[94:95]
	v_pk_add_f32 v[36:37], v[36:37], v[92:93]
	s_waitcnt vmcnt(4)
	v_pk_add_f32 v[34:35], v[34:35], v[98:99]
	v_pk_add_f32 v[32:33], v[32:33], v[96:97]
	ds_bpermute_b32 v236, v238, v50
	ds_bpermute_b32 v237, v238, v51
	ds_bpermute_b32 v240, v238, v44
	ds_bpermute_b32 v241, v238, v45
	ds_bpermute_b32 v242, v238, v46
	ds_bpermute_b32 v243, v238, v47
	ds_bpermute_b32 v244, v238, v40
	ds_bpermute_b32 v245, v238, v41
	ds_bpermute_b32 v246, v238, v42
	ds_bpermute_b32 v247, v238, v43
	s_waitcnt lgkmcnt(4)
	global_store_dwordx4 v[236:237], v[240:243], off
	ds_bpermute_b32 v248, v238, v36
	ds_bpermute_b32 v249, v238, v37
	ds_bpermute_b32 v250, v238, v38
	ds_bpermute_b32 v251, v238, v39
	s_waitcnt lgkmcnt(4)
	global_store_dwordx4 v[236:237], v[244:247], off offset:64
	ds_bpermute_b32 v252, v238, v32
	ds_bpermute_b32 v253, v238, v33
	ds_bpermute_b32 v254, v238, v34
	ds_bpermute_b32 v255, v238, v35
	s_waitcnt lgkmcnt(4)
	global_store_dwordx4 v[236:237], v[248:251], off offset:512
	s_waitcnt lgkmcnt(0)
	global_store_dwordx4 v[236:237], v[252:255], off offset:576
	global_load_dwordx4 v[44:47], v[52:53], off
	s_nop 0
	global_load_dwordx4 v[40:43], v[52:53], off offset:64
	global_load_dwordx4 v[36:39], v[52:53], off offset:512
	global_load_dwordx4 v[32:35], v[52:53], off offset:576
	v_add_u32_e32 v52, 0xb0, v156
	v_cmp_lt_i32_e32 vcc, s40, v52
	s_and_saveexec_b64 s[18:19], vcc
	s_xor_b64 s[18:19], exec, s[18:19]
	s_cbranch_execz .LBB0_1245
	v_add_u32_e32 v148, 0xffff80b0, v156
	v_readlane_b32 s44, v234, 2
	v_lshlrev_b64 v[50:51], 12, v[148:149]
	v_readlane_b32 s46, v234, 4
	v_readlane_b32 s47, v234, 5
	v_mov_b32_e32 v53, v149
	v_readlane_b32 s45, v234, 3
	v_lshl_add_u64 v[54:55], s[46:47], 0, v[50:51]
	v_lshlrev_b64 v[50:51], 12, v[52:53]
	v_readlane_b32 s48, v234, 6
	v_readlane_b32 s49, v234, 7
	v_readlane_b32 s50, v234, 8
	v_readlane_b32 s51, v234, 9
	v_readlane_b32 s52, v234, 10
	v_readlane_b32 s53, v234, 11
	v_readlane_b32 s54, v234, 12
	v_readlane_b32 s55, v234, 13
	v_readlane_b32 s56, v234, 14
	v_readlane_b32 s57, v234, 15
	v_readlane_b32 s58, v234, 16
	v_readlane_b32 s59, v234, 17

;     DEVI void operator()(const f32x4 (&acc)[2][2][4][2], const pg8::Unit& u, int wr, int wc, int l15, int g) const {
;     ...
; #pragma unroll
;             for (int m = 2 * mh; m < 2 * mh + 2; ++m) {
;                 const int tok = u.pm * 256 + 128 * ai + 64 * wr + 16 * m + l15;
;                 const float* xr = (tok < NTP) ? pp->x_p + (size_t)tok * 1024 : pp->x_s + (size_t)(tok - NTP) * 1024;
; #pragma unroll
;                 for (int bj = 0; bj < 2; ++bj)
; #pragma unroll
;                     for (int n = 0; n < 2; ++n) xv[m][bj][n] = *(const f32x4*)(xr + colb + 128 * bj + 16 * n);
;             }
; #pragma unroll
;             for (int m = 2 * mh; m < 2 * mh + 2; ++m) {
;                 const int tok = u.pm * 256 + 128 * ai + 64 * wr + 16 * m + l15;
; #pragma unroll
;                 for (int bj = 0; bj < 2; ++bj)
; #pragma unroll
;                     for (int n = 0; n < 2; ++n) *(f32x4*)(pp->out + (size_t)tok * 1024 + colb + 128 * bj + 16 * n) = xv[m][bj][n] + acc[ai][bj][m][n];
;             }
.LBB0_1247:
	s_or_b64 exec, exec, s[18:19]
	v_lshl_add_u64 v[68:69], v[54:55], 0, v[154:155]
	global_load_dwordx4 v[52:55], v[68:69], off
	global_load_dwordx4 v[56:59], v[68:69], off offset:64
	global_load_dwordx4 v[60:63], v[68:69], off offset:512
	global_load_dwordx4 v[64:67], v[68:69], off offset:576
	v_readlane_b32 s44, v234, 24
	v_readlane_b32 s58, v234, 38
	v_readlane_b32 s59, v234, 39
	v_lshlrev_b64 v[48:49], 12, v[48:49]
	s_mov_b64 s[18:19], s[58:59]
	s_waitcnt vmcnt(4)
	v_pk_add_f32 v[18:19], v[18:19], v[34:35]
	v_pk_add_f32 v[16:17], v[16:17], v[32:33]
	v_lshl_add_u64 v[32:33], s[18:19], 0, v[50:51]
	v_lshl_add_u64 v[34:35], s[18:19], 0, v[48:49]
	v_pk_add_f32 v[30:31], v[30:31], v[46:47]
	v_pk_add_f32 v[28:29], v[28:29], v[44:45]
	v_lshl_add_u64 v[32:33], v[32:33], 0, v[154:155]
	v_lshl_add_u64 v[34:35], v[34:35], 0, v[154:155]
	s_andn2_b64 vcc, exec, s[16:17]
	s_mov_b64 s[16:17], -1
	v_pk_add_f32 v[26:27], v[26:27], v[42:43]
	v_pk_add_f32 v[24:25], v[24:25], v[40:41]
	v_pk_add_f32 v[22:23], v[22:23], v[38:39]
	v_pk_add_f32 v[20:21], v[20:21], v[36:37]
	v_readlane_b32 s45, v234, 25
	v_readlane_b32 s46, v234, 26
	v_readlane_b32 s47, v234, 27
	v_readlane_b32 s48, v234, 28
	v_readlane_b32 s49, v234, 29
	v_readlane_b32 s50, v234, 30
	v_readlane_b32 s51, v234, 31
	v_readlane_b32 s52, v234, 32
	v_readlane_b32 s53, v234, 33
	v_readlane_b32 s54, v234, 34
	v_readlane_b32 s55, v234, 35
	v_readlane_b32 s56, v234, 36
	v_readlane_b32 s57, v234, 37
	ds_bpermute_b32 v236, v238, v34
	ds_bpermute_b32 v237, v238, v35
	ds_bpermute_b32 v240, v238, v28
	ds_bpermute_b32 v241, v238, v29
	ds_bpermute_b32 v242, v238, v30
	ds_bpermute_b32 v243, v238, v31
	ds_bpermute_b32 v244, v238, v24
	ds_bpermute_b32 v245, v238, v25
	ds_bpermute_b32 v246, v238, v26
	ds_bpermute_b32 v247, v238, v27
	s_waitcnt lgkmcnt(4)
	global_store_dwordx4 v[236:237], v[240:243], off
	ds_bpermute_b32 v248, v238, v20
	ds_bpermute_b32 v249, v238, v21
	ds_bpermute_b32 v250, v238, v22
	ds_bpermute_b32 v251, v238, v23
	s_waitcnt lgkmcnt(4)
	global_store_dwordx4 v[236:237], v[244:247], off offset:64
	ds_bpermute_b32 v252, v238, v16
	ds_bpermute_b32 v253, v238, v17
	ds_bpermute_b32 v254, v238, v18
	ds_bpermute_b32 v255, v238, v19
	s_waitcnt lgkmcnt(4)
	global_store_dwordx4 v[236:237], v[248:251], off offset:512
	s_waitcnt lgkmcnt(0)
	global_store_dwordx4 v[236:237], v[252:255], off offset:576
	s_waitcnt vmcnt(7)
	v_pk_add_f32 v[14:15], v[14:15], v[54:55]
	v_pk_add_f32 v[12:13], v[12:13], v[52:53]
	s_waitcnt vmcnt(6)
	v_pk_add_f32 v[10:11], v[10:11], v[58:59]
	v_pk_add_f32 v[8:9], v[8:9], v[56:57]
	s_waitcnt vmcnt(5)
	v_pk_add_f32 v[6:7], v[6:7], v[62:63]
	v_pk_add_f32 v[4:5], v[4:5], v[60:61]
	s_waitcnt vmcnt(4)
	v_pk_add_f32 v[2:3], v[2:3], v[66:67]
	v_pk_add_f32 v[0:1], v[0:1], v[64:65]
	ds_bpermute_b32 v236, v238, v32
	ds_bpermute_b32 v237, v238, v33
	ds_bpermute_b32 v240, v238, v12
	ds_bpermute_b32 v241, v238, v13
	ds_bpermute_b32 v242, v238, v14
	ds_bpermute_b32 v243, v238, v15
	ds_bpermute_b32 v244, v238, v8
	ds_bpermute_b32 v245, v238, v9
	ds_bpermute_b32 v246, v238, v10
	ds_bpermute_b32 v247, v238, v11
	s_waitcnt lgkmcnt(4)
	global_store_dwordx4 v[236:237], v[240:243], off
	ds_bpermute_b32 v248, v238, v4
	ds_bpermute_b32 v249, v238, v5
	ds_bpermute_b32 v250, v238, v6
	ds_bpermute_b32 v251, v238, v7
	s_waitcnt lgkmcnt(4)
	global_store_dwordx4 v[236:237], v[244:247], off offset:64
	ds_bpermute_b32 v252, v238, v0
	ds_bpermute_b32 v253, v238, v1
	ds_bpermute_b32 v254, v238, v2
	ds_bpermute_b32 v255, v238, v3
	s_waitcnt lgkmcnt(4)
	global_store_dwordx4 v[236:237], v[248:251], off offset:512
	s_waitcnt lgkmcnt(0)
	global_store_dwordx4 v[236:237], v[252:255], off offset:576
	s_cbranch_vccnz .LBB0_1221
	s_andn2_b64 vcc, exec, s[0:1]
	s_cbranch_vccnz .LBB0_1220
	s_barrier
	s_branch .LBB0_1220
